# v25 + first grid barrier: the 16 per-XCD arrival counts loaded together (prologue de-serialisation) instead of 16 serialized round trips
# speedup vs baseline: 1.0029x; 1.0029x over previous
; __device__ __forceinline__ unsigned xb_ld(unsigned* p)              { return __hip_atomic_load(p, __ATOMIC_RELAXED, __HIP_MEMORY_SCOPE_AGENT); }
; __device__ __forceinline__ void xcd_barrier_complete(unsigned* bar, unsigned x, unsigned& nloc, unsigned& nx) {
;     const unsigned G = gridDim.x * gridDim.y * gridDim.z;
;     unsigned sum, cnt, mine, sp = 0u;
;     for (;;) {
;         sum = 0u; cnt = 0u; mine = 0u;
; #pragma unroll
;         for (unsigned j = 0; j < 16; ++j) { const unsigned c = xb_ld(&bar[XB_XCNT(j)]); sum += c; cnt += (c > 0u) ? 1u : 0u; mine = (j == x) ? c : mine; }
;         if (sum == G) break;
;         __builtin_amdgcn_s_sleep(1);
;         if ((++sp & 255u) == 0u) { if (xb_ld(&bar[XB_TMO])) break; if (sp > XB_SPIN_CAP) { atomicAdd(&bar[XB_TMO], 1u); break; } }
;     }
;     nloc = mine > 0u ? mine : 1u; nx = cnt > 0u ? cnt : 1u;
; }
.LBB0_1059:
	v_readlane_b32 s0, v252, 51
	v_readlane_b32 s1, v252, 52
	v_readlane_b32 s3, v252, 17
	s_mov_b64 s[22:23], -1
	s_waitcnt lgkmcnt(0)
	s_nop 3
	global_load_dword v0, v1, s[0:1] sc1
	global_load_dword v2, v1, s[0:1] offset:256 sc1
	global_load_dword v3, v1, s[0:1] offset:512 sc1
	global_load_dword v4, v1, s[0:1] offset:768 sc1
	global_load_dword v5, v1, s[0:1] offset:1024 sc1
	global_load_dword v6, v1, s[0:1] offset:1280 sc1
	global_load_dword v7, v1, s[0:1] offset:1536 sc1
	global_load_dword v8, v1, s[0:1] offset:1792 sc1
	global_load_dword v9, v1, s[0:1] offset:2048 sc1
	global_load_dword v10, v1, s[0:1] offset:2304 sc1
	global_load_dword v11, v1, s[0:1] offset:2560 sc1
	global_load_dword v12, v1, s[0:1] offset:2816 sc1
	global_load_dword v13, v1, s[0:1] offset:3072 sc1
	global_load_dword v14, v1, s[0:1] offset:3328 sc1
	global_load_dword v15, v1, s[0:1] offset:3584 sc1
	global_load_dword v16, v1, s[0:1] offset:3840 sc1
	s_mov_b64 s[0:1], -1
	s_waitcnt vmcnt(0)
	v_add_u32_e32 v17, v2, v0
	v_add_u32_e32 v17, v17, v3
	v_add_u32_e32 v17, v17, v4
	v_add_u32_e32 v17, v17, v5
	v_add_u32_e32 v17, v17, v6
	v_add_u32_e32 v17, v17, v7
	v_add_u32_e32 v17, v17, v8
	v_add_u32_e32 v17, v17, v9
	v_add_u32_e32 v17, v17, v10
	v_add_u32_e32 v17, v17, v11
	v_add_u32_e32 v17, v17, v12
	v_add_u32_e32 v17, v17, v13
	v_add_u32_e32 v17, v17, v14
	v_add_u32_e32 v17, v17, v15
	v_add_u32_e32 v17, v17, v16
	v_cmp_eq_u32_e32 vcc, s3, v17
	s_cbranch_vccnz .LBB0_1058
	s_and_b32 s0, s2, 0xff
	s_cmp_eq_u32 s0, 0
	s_mov_b64 s[0:1], -1
	s_mov_b64 s[24:25], -1
	s_sleep 1
	s_cbranch_scc0 .LBB0_1063
	v_readlane_b32 s0, v252, 49
	v_readlane_b32 s1, v252, 50
	s_nop 4
	global_load_dword v17, v1, s[0:1] sc1
	s_waitcnt vmcnt(0)
	v_cmp_eq_u32_e32 vcc, 0, v17
	s_cbranch_vccnz .LBB0_1065
	s_mov_b64 s[24:25], 0
	s_mov_b64 s[0:1], -1
